# BAR-MATH-HOIST: grid-barrier XCD-arrival reciprocal chain computed while the arrival atomic is in flight (on REL-FIRST)
# baseline (speedup 1.0000x reference)
.LBB0_60:
	s_or_b64 exec, exec, s[12:13]
	v_cvt_f32_u32_e32 v5, v3
	v_rcp_iflag_f32_e32 v5, v5
	s_nop 0
	v_mul_f32_e32 v5, 0x4f7ffffe, v5
	v_cvt_u32_f32_e32 v5, v5
	s_waitcnt vmcnt(0)
	v_readfirstlane_b32 s0, v4
	v_sub_u32_e32 v4, 0, v3
	s_nop 0
	v_add_u32_e32 v6, s0, v2
	v_mul_lo_u32 v2, v4, v5
	v_mul_hi_u32 v2, v5, v2
	v_add_u32_e32 v2, v5, v2
	v_mul_hi_u32 v2, v6, v2
	v_mul_lo_u32 v4, v2, v3
	v_sub_u32_e32 v4, v6, v4
	v_add_u32_e32 v5, 1, v2
	v_cmp_ge_u32_e32 vcc, v4, v3
	s_nop 1
	v_cndmask_b32_e32 v2, v2, v5, vcc
	v_sub_u32_e32 v5, v4, v3
	v_cndmask_b32_e32 v4, v4, v5, vcc
	v_add_u32_e32 v5, 1, v2
	v_cmp_ge_u32_e32 vcc, v4, v3
	v_add_u32_e32 v4, 1, v6
	s_nop 0
	v_cndmask_b32_e32 v2, v2, v5, vcc
	v_mul_lo_u32 v5, v3, v2
	v_add_u32_e32 v3, v5, v3
	v_cmp_ne_u32_e32 vcc, v4, v3
	s_and_saveexec_b64 s[0:1], vcc
	s_xor_b64 s[10:11], exec, s[0:1]
	s_cbranch_execz .LBB0_74
	buffer_inv sc1
	s_waitcnt lgkmcnt(0)
	v_mov_b32_e32 v1, 0x2000
	global_load_dword v1, v1, s[8:9] offset:1024 sc1
	s_add_u32 s16, s8, 0x2400
	s_addc_u32 s17, s9, 0
	s_waitcnt vmcnt(0)
	v_cmp_eq_u32_e32 vcc, v1, v2
	s_and_saveexec_b64 s[12:13], vcc
	s_cbranch_execz .LBB0_73
	v_readlane_b32 s0, v255, 5
	v_readlane_b32 s1, v255, 6
	s_add_u32 s14, s0, 0x1200
	s_addc_u32 s15, s1, 0
	s_mov_b32 s0, 1
	s_mov_b64 s[18:19], 0
	v_mov_b32_e32 v1, 0
	s_branch .LBB0_64
